# hot loop heads (8 GEMM K-loops, attention steady loop) aligned to 64 bytes with .p2align 6
# speedup vs baseline: 1.0166x; 1.0138x over previous
;     __host__ __device__ bool next(int i, Unit& u) const { if (i >= 2) return false; u.pm = 32 * i + (v >> 3); u.pn = v & 7; return true; }
; template <class Epi, class Sched, bool ALIGN_EPI = false, bool SP2 = false>
; __device__ __forceinline__ void gemm_phase(PG8_LAS unsigned char* lds, const Gemm g, const Sched& S, const Epi& E) {
;     ...
;         const bool has_next = S.next(ui + 1, nxt);
;         const char* nA = has_next ? (const char*)g.A + (size_t)nxt.pm * tstep : cA; const char* nB = has_next ? (const char*)g.Bt + (size_t)nxt.pn * tstep : cB;
;         for (int t = 0; t < nt; t += 2) {
;             const bool last = (t == nt - 2);
;             const char* a1 = cA + (size_t)(t + 1) * kstep;
;             const char* a2 = last ? nA : cA + (size_t)(t + 2) * kstep; const char* b2 = last ? nB : cB + (size_t)(t + 2) * kstep;
;     ...
; #pragma unroll
;         for (int a = 0; a < 2; ++a)
; #pragma unroll
;             for (int b = 0; b < 2; ++b)
; #pragma unroll
;                 for (int m = 0; m < 4; ++m)
; #pragma unroll
;                     for (int n = 0; n < 2; ++n) acc[a][b][m][n] = (f32x4){0.f, 0.f, 0.f, 0.f};
.LBB0_94:
	s_ashr_i32 s23, s22, 31
	s_lshl_b64 s[24:25], s[22:23], 20
	s_add_u32 s24, s70, s24
	s_addc_u32 s25, s71, s25
	s_and_b64 s[52:53], s[6:7], exec
	s_cselect_b32 s23, s25, s81
	s_cselect_b32 s52, s24, s80
	s_ashr_i32 s21, s20, 31
	s_lshl_b64 s[54:55], s[20:21], 20
	v_readlane_b32 s48, v250, 4
	v_readlane_b32 s49, v250, 5
	s_add_u32 s74, s48, s54
	s_addc_u32 s75, s49, s55
	s_and_b64 s[54:55], s[6:7], exec
	s_cselect_b32 s21, s75, s1
	s_cselect_b32 s53, s74, s0
	s_add_u32 s80, s80, 0x80080
	s_addc_u32 s81, s81, 0
	s_add_u32 s54, s0, 0x100
	v_mov_b32_e32 v0, 0
	s_addc_u32 s55, s1, 0
	s_mov_b32 s56, -2
	v_mov_b32_e32 v1, v0
	v_mov_b32_e32 v2, v0
	v_mov_b32_e32 v3, v0
	v_mov_b32_e32 v4, v0
	v_mov_b32_e32 v5, v0
	v_mov_b32_e32 v6, v0
	v_mov_b32_e32 v7, v0
	v_mov_b32_e32 v16, v0
	v_mov_b32_e32 v17, v0
	v_mov_b32_e32 v18, v0
	v_mov_b32_e32 v19, v0
	v_mov_b32_e32 v20, v0
	v_mov_b32_e32 v21, v0
	v_mov_b32_e32 v22, v0
	v_mov_b32_e32 v23, v0
	v_mov_b32_e32 v32, v0
	v_mov_b32_e32 v33, v0
	v_mov_b32_e32 v34, v0
	v_mov_b32_e32 v35, v0
	v_mov_b32_e32 v36, v0
	v_mov_b32_e32 v37, v0
	v_mov_b32_e32 v38, v0
	v_mov_b32_e32 v39, v0
	v_mov_b32_e32 v48, v0
	v_mov_b32_e32 v49, v0
	v_mov_b32_e32 v50, v0
	v_mov_b32_e32 v51, v0
	v_mov_b32_e32 v52, v0
	v_mov_b32_e32 v53, v0
	v_mov_b32_e32 v54, v0
	v_mov_b32_e32 v55, v0
	v_mov_b32_e32 v8, v0
	v_mov_b32_e32 v9, v0
	v_mov_b32_e32 v10, v0
	v_mov_b32_e32 v11, v0
	v_mov_b32_e32 v12, v0
	v_mov_b32_e32 v13, v0
	v_mov_b32_e32 v14, v0
	v_mov_b32_e32 v15, v0
	v_mov_b32_e32 v24, v0
	v_mov_b32_e32 v25, v0
	v_mov_b32_e32 v26, v0
	v_mov_b32_e32 v27, v0
	v_mov_b32_e32 v28, v0
	v_mov_b32_e32 v29, v0
	v_mov_b32_e32 v30, v0
	v_mov_b32_e32 v31, v0
	v_mov_b32_e32 v40, v0
	v_mov_b32_e32 v41, v0
	v_mov_b32_e32 v42, v0
	v_mov_b32_e32 v43, v0
	v_mov_b32_e32 v44, v0
	v_mov_b32_e32 v45, v0
	v_mov_b32_e32 v46, v0
	v_mov_b32_e32 v47, v0
	v_mov_b32_e32 v56, v0
	v_mov_b32_e32 v57, v0
	v_mov_b32_e32 v58, v0
	v_mov_b32_e32 v59, v0
	v_mov_b32_e32 v60, v0
	v_mov_b32_e32 v61, v0
	v_mov_b32_e32 v62, v0
	v_mov_b32_e32 v63, v0
	v_mov_b32_e32 v64, v0
	v_mov_b32_e32 v65, v0
	v_mov_b32_e32 v66, v0
	v_mov_b32_e32 v67, v0
	v_mov_b32_e32 v68, v0
	v_mov_b32_e32 v69, v0
	v_mov_b32_e32 v70, v0
	v_mov_b32_e32 v71, v0
	v_mov_b32_e32 v80, v0
	v_mov_b32_e32 v81, v0
	v_mov_b32_e32 v82, v0
	v_mov_b32_e32 v83, v0
	v_mov_b32_e32 v84, v0
	v_mov_b32_e32 v85, v0
	v_mov_b32_e32 v86, v0
	v_mov_b32_e32 v87, v0
	v_mov_b32_e32 v96, v0
	v_mov_b32_e32 v97, v0
	v_mov_b32_e32 v98, v0
	v_mov_b32_e32 v99, v0
	v_mov_b32_e32 v100, v0
	v_mov_b32_e32 v101, v0
	v_mov_b32_e32 v102, v0
	v_mov_b32_e32 v103, v0
	v_mov_b32_e32 v112, v0
	v_mov_b32_e32 v113, v0
	v_mov_b32_e32 v114, v0
	v_mov_b32_e32 v115, v0
	v_mov_b32_e32 v116, v0
	v_mov_b32_e32 v117, v0
	v_mov_b32_e32 v118, v0
	v_mov_b32_e32 v119, v0
	v_mov_b32_e32 v72, v0
	v_mov_b32_e32 v73, v0
	v_mov_b32_e32 v74, v0
	v_mov_b32_e32 v75, v0
	v_mov_b32_e32 v76, v0
	v_mov_b32_e32 v77, v0
	v_mov_b32_e32 v78, v0
	v_mov_b32_e32 v79, v0
	v_mov_b32_e32 v88, v0
	v_mov_b32_e32 v89, v0
	v_mov_b32_e32 v90, v0
	v_mov_b32_e32 v91, v0
	v_mov_b32_e32 v92, v0
	v_mov_b32_e32 v93, v0
	v_mov_b32_e32 v94, v0
	v_mov_b32_e32 v95, v0
	v_mov_b32_e32 v104, v0
	v_mov_b32_e32 v105, v0
	v_mov_b32_e32 v106, v0
	v_mov_b32_e32 v107, v0
	v_mov_b32_e32 v108, v0
	v_mov_b32_e32 v109, v0
	v_mov_b32_e32 v110, v0
	v_mov_b32_e32 v111, v0
	v_mov_b32_e32 v120, v0
	v_mov_b32_e32 v121, v0
	v_mov_b32_e32 v122, v0
	v_mov_b32_e32 v123, v0
	v_mov_b32_e32 v124, v0
	v_mov_b32_e32 v125, v0
	v_mov_b32_e32 v126, v0
	v_mov_b32_e32 v127, v0
	.p2align	6

;     __host__ __device__ bool next(int i, Unit& u) const { if (i >= 2) return false; u.pm = 32 * i + (v >> 3); u.pn = v & 7; return true; }
; template <class Epi, class Sched, bool ALIGN_EPI = false, bool SP2 = false>
; __device__ __forceinline__ void gemm_phase(PG8_LAS unsigned char* lds, const Gemm g, const Sched& S, const Epi& E) {
;     ...
;         const bool has_next = S.next(ui + 1, nxt);
;         const char* nA = has_next ? (const char*)g.A + (size_t)nxt.pm * tstep : cA; const char* nB = has_next ? (const char*)g.Bt + (size_t)nxt.pn * tstep : cB;
;         for (int t = 0; t < nt; t += 2) {
;             const bool last = (t == nt - 2);
;             const char* a1 = cA + (size_t)(t + 1) * kstep;
;             const char* a2 = last ? nA : cA + (size_t)(t + 2) * kstep; const char* b2 = last ? nB : cB + (size_t)(t + 2) * kstep;
;     ...
; #pragma unroll
;         for (int a = 0; a < 2; ++a)
; #pragma unroll
;             for (int b = 0; b < 2; ++b)
; #pragma unroll
;                 for (int m = 0; m < 4; ++m)
; #pragma unroll
;                     for (int n = 0; n < 2; ++n) acc[a][b][m][n] = (f32x4){0.f, 0.f, 0.f, 0.f};
.LBB0_176:
	s_add_u32 s54, s0, 0x100
	v_mov_b32_e32 v0, 0
	s_addc_u32 s55, s1, 0
	s_mov_b32 s56, -2
	s_waitcnt lgkmcnt(0)
	v_mov_b32_e32 v1, v0
	v_mov_b32_e32 v2, v0
	v_mov_b32_e32 v3, v0
	v_mov_b32_e32 v4, v0
	v_mov_b32_e32 v5, v0
	v_mov_b32_e32 v6, v0
	v_mov_b32_e32 v7, v0
	v_mov_b32_e32 v16, v0
	v_mov_b32_e32 v17, v0
	v_mov_b32_e32 v18, v0
	v_mov_b32_e32 v19, v0
	v_mov_b32_e32 v20, v0
	v_mov_b32_e32 v21, v0
	v_mov_b32_e32 v22, v0
	v_mov_b32_e32 v23, v0
	v_mov_b32_e32 v32, v0
	v_mov_b32_e32 v33, v0
	v_mov_b32_e32 v34, v0
	v_mov_b32_e32 v35, v0
	v_mov_b32_e32 v36, v0
	v_mov_b32_e32 v37, v0
	v_mov_b32_e32 v38, v0
	v_mov_b32_e32 v39, v0
	v_mov_b32_e32 v48, v0
	v_mov_b32_e32 v49, v0
	v_mov_b32_e32 v50, v0
	v_mov_b32_e32 v51, v0
	v_mov_b32_e32 v52, v0
	v_mov_b32_e32 v53, v0
	v_mov_b32_e32 v54, v0
	v_mov_b32_e32 v55, v0
	v_mov_b32_e32 v8, v0
	v_mov_b32_e32 v9, v0
	v_mov_b32_e32 v10, v0
	v_mov_b32_e32 v11, v0
	v_mov_b32_e32 v12, v0
	v_mov_b32_e32 v13, v0
	v_mov_b32_e32 v14, v0
	v_mov_b32_e32 v15, v0
	v_mov_b32_e32 v24, v0
	v_mov_b32_e32 v25, v0
	v_mov_b32_e32 v26, v0
	v_mov_b32_e32 v27, v0
	v_mov_b32_e32 v28, v0
	v_mov_b32_e32 v29, v0
	v_mov_b32_e32 v30, v0
	v_mov_b32_e32 v31, v0
	v_mov_b32_e32 v40, v0
	v_mov_b32_e32 v41, v0
	v_mov_b32_e32 v42, v0
	v_mov_b32_e32 v43, v0
	v_mov_b32_e32 v44, v0
	v_mov_b32_e32 v45, v0
	v_mov_b32_e32 v46, v0
	v_mov_b32_e32 v47, v0
	v_mov_b32_e32 v56, v0
	v_mov_b32_e32 v57, v0
	v_mov_b32_e32 v58, v0
	v_mov_b32_e32 v59, v0
	v_mov_b32_e32 v60, v0
	v_mov_b32_e32 v61, v0
	v_mov_b32_e32 v62, v0
	v_mov_b32_e32 v63, v0
	v_mov_b32_e32 v64, v0
	v_mov_b32_e32 v65, v0
	v_mov_b32_e32 v66, v0
	v_mov_b32_e32 v67, v0
	v_mov_b32_e32 v68, v0
	v_mov_b32_e32 v69, v0
	v_mov_b32_e32 v70, v0
	v_mov_b32_e32 v71, v0
	v_mov_b32_e32 v80, v0
	v_mov_b32_e32 v81, v0
	v_mov_b32_e32 v82, v0
	v_mov_b32_e32 v83, v0
	v_mov_b32_e32 v84, v0
	v_mov_b32_e32 v85, v0
	v_mov_b32_e32 v86, v0
	v_mov_b32_e32 v87, v0
	v_mov_b32_e32 v96, v0
	v_mov_b32_e32 v97, v0
	v_mov_b32_e32 v98, v0
	v_mov_b32_e32 v99, v0
	v_mov_b32_e32 v100, v0
	v_mov_b32_e32 v101, v0
	v_mov_b32_e32 v102, v0
	v_mov_b32_e32 v103, v0
	v_mov_b32_e32 v112, v0
	v_mov_b32_e32 v113, v0
	v_mov_b32_e32 v114, v0
	v_mov_b32_e32 v115, v0
	v_mov_b32_e32 v116, v0
	v_mov_b32_e32 v117, v0
	v_mov_b32_e32 v118, v0
	v_mov_b32_e32 v119, v0
	v_mov_b32_e32 v72, v0
	v_mov_b32_e32 v73, v0
	v_mov_b32_e32 v74, v0
	v_mov_b32_e32 v75, v0
	v_mov_b32_e32 v76, v0
	v_mov_b32_e32 v77, v0
	v_mov_b32_e32 v78, v0
	v_mov_b32_e32 v79, v0
	v_mov_b32_e32 v88, v0
	v_mov_b32_e32 v89, v0
	v_mov_b32_e32 v90, v0
	v_mov_b32_e32 v91, v0
	v_mov_b32_e32 v92, v0
	v_mov_b32_e32 v93, v0
	v_mov_b32_e32 v94, v0
	v_mov_b32_e32 v95, v0
	v_mov_b32_e32 v104, v0
	v_mov_b32_e32 v105, v0
	v_mov_b32_e32 v106, v0
	v_mov_b32_e32 v107, v0
	v_mov_b32_e32 v108, v0
	v_mov_b32_e32 v109, v0
	v_mov_b32_e32 v110, v0
	v_mov_b32_e32 v111, v0
	v_mov_b32_e32 v120, v0
	v_mov_b32_e32 v121, v0
	v_mov_b32_e32 v122, v0
	v_mov_b32_e32 v123, v0
	v_mov_b32_e32 v124, v0
	v_mov_b32_e32 v125, v0
	v_mov_b32_e32 v126, v0
	v_mov_b32_e32 v127, v0
	.p2align	6

;     __host__ __device__ bool next(int i, Unit& u) const { if (i >= 2) return false; u.pm = 32 * i + (v >> 3); u.pn = v & 7; return true; }
; template <class Epi, class Sched, bool ALIGN_EPI = false, bool SP2 = false>
; __device__ __forceinline__ void gemm_phase(PG8_LAS unsigned char* lds, const Gemm g, const Sched& S, const Epi& E) {
;     ...
;         const bool has_next = S.next(ui + 1, nxt);
;         const char* nA = has_next ? (const char*)g.A + (size_t)nxt.pm * tstep : cA; const char* nB = has_next ? (const char*)g.Bt + (size_t)nxt.pn * tstep : cB;
;         for (int t = 0; t < nt; t += 2) {
;             const bool last = (t == nt - 2);
;             const char* a1 = cA + (size_t)(t + 1) * kstep;
;             const char* a2 = last ? nA : cA + (size_t)(t + 2) * kstep; const char* b2 = last ? nB : cB + (size_t)(t + 2) * kstep;
;     ...
; #pragma unroll
;         for (int a = 0; a < 2; ++a)
; #pragma unroll
;             for (int b = 0; b < 2; ++b)
; #pragma unroll
;                 for (int m = 0; m < 4; ++m)
; #pragma unroll
;                     for (int n = 0; n < 2; ++n) acc[a][b][m][n] = (f32x4){0.f, 0.f, 0.f, 0.f};
.LBB0_262:
	s_ashr_i32 s95, s94, 31
	s_lshl_b64 s[6:7], s[94:95], 20
	s_add_u32 s96, s70, s6
	s_addc_u32 s97, s71, s7
	s_and_b64 s[6:7], s[8:9], exec
	s_cselect_b32 s3, s97, s5
	s_cselect_b32 s11, s96, s4
	s_ashr_i32 s93, s92, 31
	s_lshl_b64 s[6:7], s[92:93], 20
	s_add_u32 s74, s18, s6
	s_addc_u32 s75, s19, s7
	s_and_b64 s[6:7], s[8:9], exec
	s_cselect_b32 s12, s75, s1
	s_cselect_b32 s13, s74, s0
	s_add_u32 s4, s4, 0x80080
	s_addc_u32 s5, s5, 0
	s_add_u32 s15, s0, 0x100
	v_mov_b32_e32 v0, 0
	s_addc_u32 s16, s1, 0
	s_mov_b32 s17, -2
	v_mov_b32_e32 v1, v0
	v_mov_b32_e32 v2, v0
	v_mov_b32_e32 v3, v0
	v_mov_b32_e32 v8, v0
	v_mov_b32_e32 v9, v0
	v_mov_b32_e32 v10, v0
	v_mov_b32_e32 v11, v0
	v_mov_b32_e32 v32, v0
	v_mov_b32_e32 v33, v0
	v_mov_b32_e32 v34, v0
	v_mov_b32_e32 v35, v0
	v_mov_b32_e32 v36, v0
	v_mov_b32_e32 v37, v0
	v_mov_b32_e32 v38, v0
	v_mov_b32_e32 v39, v0
	v_mov_b32_e32 v48, v0
	v_mov_b32_e32 v49, v0
	v_mov_b32_e32 v50, v0
	v_mov_b32_e32 v51, v0
	v_mov_b32_e32 v52, v0
	v_mov_b32_e32 v53, v0
	v_mov_b32_e32 v54, v0
	v_mov_b32_e32 v55, v0
	v_mov_b32_e32 v64, v0
	v_mov_b32_e32 v65, v0
	v_mov_b32_e32 v66, v0
	v_mov_b32_e32 v67, v0
	v_mov_b32_e32 v68, v0
	v_mov_b32_e32 v69, v0
	v_mov_b32_e32 v70, v0
	v_mov_b32_e32 v71, v0
	v_mov_b32_e32 v24, v0
	v_mov_b32_e32 v25, v0
	v_mov_b32_e32 v26, v0
	v_mov_b32_e32 v27, v0
	v_mov_b32_e32 v28, v0
	v_mov_b32_e32 v29, v0
	v_mov_b32_e32 v30, v0
	v_mov_b32_e32 v31, v0
	v_mov_b32_e32 v40, v0
	v_mov_b32_e32 v41, v0
	v_mov_b32_e32 v42, v0
	v_mov_b32_e32 v43, v0
	v_mov_b32_e32 v44, v0
	v_mov_b32_e32 v45, v0
	v_mov_b32_e32 v46, v0
	v_mov_b32_e32 v47, v0
	v_mov_b32_e32 v56, v0
	v_mov_b32_e32 v57, v0
	v_mov_b32_e32 v58, v0
	v_mov_b32_e32 v59, v0
	v_mov_b32_e32 v60, v0
	v_mov_b32_e32 v61, v0
	v_mov_b32_e32 v62, v0
	v_mov_b32_e32 v63, v0
	v_mov_b32_e32 v72, v0
	v_mov_b32_e32 v73, v0
	v_mov_b32_e32 v74, v0
	v_mov_b32_e32 v75, v0
	v_mov_b32_e32 v76, v0
	v_mov_b32_e32 v77, v0
	v_mov_b32_e32 v78, v0
	v_mov_b32_e32 v79, v0
	v_mov_b32_e32 v80, v0
	v_mov_b32_e32 v81, v0
	v_mov_b32_e32 v82, v0
	v_mov_b32_e32 v83, v0
	v_mov_b32_e32 v84, v0
	v_mov_b32_e32 v85, v0
	v_mov_b32_e32 v86, v0
	v_mov_b32_e32 v87, v0
	v_mov_b32_e32 v96, v0
	v_mov_b32_e32 v97, v0
	v_mov_b32_e32 v98, v0
	v_mov_b32_e32 v99, v0
	v_mov_b32_e32 v100, v0
	v_mov_b32_e32 v101, v0
	v_mov_b32_e32 v102, v0
	v_mov_b32_e32 v103, v0
	v_mov_b32_e32 v112, v0
	v_mov_b32_e32 v113, v0
	v_mov_b32_e32 v114, v0
	v_mov_b32_e32 v115, v0
	v_mov_b32_e32 v116, v0
	v_mov_b32_e32 v117, v0
	v_mov_b32_e32 v118, v0
	v_mov_b32_e32 v119, v0
	v_mov_b32_e32 v128, v0
	v_mov_b32_e32 v129, v0
	v_mov_b32_e32 v130, v0
	v_mov_b32_e32 v131, v0
	v_mov_b32_e32 v132, v0
	v_mov_b32_e32 v133, v0
	v_mov_b32_e32 v134, v0
	v_mov_b32_e32 v135, v0
	v_mov_b32_e32 v88, v0
	v_mov_b32_e32 v89, v0
	v_mov_b32_e32 v90, v0
	v_mov_b32_e32 v91, v0
	v_mov_b32_e32 v92, v0
	v_mov_b32_e32 v93, v0
	v_mov_b32_e32 v94, v0
	v_mov_b32_e32 v95, v0
	v_mov_b32_e32 v104, v0
	v_mov_b32_e32 v105, v0
	v_mov_b32_e32 v106, v0
	v_mov_b32_e32 v107, v0
	v_mov_b32_e32 v108, v0
	v_mov_b32_e32 v109, v0
	v_mov_b32_e32 v110, v0
	v_mov_b32_e32 v111, v0
	v_mov_b32_e32 v120, v0
	v_mov_b32_e32 v121, v0
	v_mov_b32_e32 v122, v0
	v_mov_b32_e32 v123, v0
	v_mov_b32_e32 v124, v0
	v_mov_b32_e32 v125, v0
	v_mov_b32_e32 v126, v0
	v_mov_b32_e32 v127, v0
	v_mov_b32_e32 v136, v0
	v_mov_b32_e32 v137, v0
	v_mov_b32_e32 v138, v0
	v_mov_b32_e32 v139, v0
	v_mov_b32_e32 v140, v0
	v_mov_b32_e32 v141, v0
	v_mov_b32_e32 v142, v0
	v_mov_b32_e32 v143, v0
	.p2align	6

; #define WAIT_BAR(N) asm volatile("s_waitcnt vmcnt(" #N ") lgkmcnt(0)\n\ts_barrier":::"memory")
;   #define DMA_K(t,slot) glds16(ksrc+(long)(t)*KVBLK*DM,(unsigned)__builtin_amdgcn_readfirstlane(kdst+(slot)))
;   #define DMA_V(t,slot) glds16(vsrc+(long)(t)*KVBLK*DM,(unsigned)__builtin_amdgcn_readfirstlane(vdst+(slot)))
;   #define CMASK(P0,P1,t) do{int jb_=(t)-(NT-4); if(jb_>=0)cmask(P0,P1,jb_,qrel,hi);}while(0)
;   #define START(P0,P1) do{ const float rm=rowmax(P0,P1); resc=false; \
;     { const float dl=rm; mhat=fadd_s(mhat,dl); \
;       _Pragma("unroll") for(int r=0;r<16;++r){P0[r]=fsub_s(P0[r],dl);P1[r]=fsub_s(P1[r],dl);} \
;       _Pragma("unroll") for(int r=0;r<16;++r)negm[r]=-mhat; asm volatile("":"+v"(negm)); } \
;     _Pragma("unroll") for(int r=0;r<16;++r)P0[r]=__builtin_amdgcn_exp2f(P0[r]); }while(0)
;   #define ROT() do{sl_prev=sl_cur;sl_cur=sl_next;sl_next=(sl_next==(NSLOT-1)*SLOTB)?0:sl_next+SLOTB;}while(0)
;   #define CMASK(P0,P1,t) do{}while(0)
;   #define CMASK(P0,P1,t) do{int jb_=(t)-(NT-4); if(jb_>=0)cmask(P0,P1,jb_,qrel,hi);}while(0)
; template<int THRL> __device__ __forceinline__ void attn_unit(int b,int h,int hv,int qb,const bf16*Q,const bf16*__restrict__ K,const bf16*__restrict__ V,bf16*O,char*shm){
;     ...
;   DMA_K(2,2*SLOTB);
;   WAIT_BAR(3);
;   qkt(pA0,pA1,Kbase,qr,negm,r32,hi);asm volatile("s_nop 15\n\ts_nop 7":"+v"(pA0),"+v"(pA1));CMASK(pA0,pA1,0);
;   START(pA0,pA1);
;   _Pragma("unroll") for(int r=0;r<16;++r)pA1[r]=__builtin_amdgcn_exp2f(pA1[r]);
;   WAIT_BAR(0);
;   DMA_K(3,0);DMA_V(1,SLOTB);
;   ROT();
;   kload8(kf,kp0+sl_cur);
;   WAIT_BAR(2);
.LBB0_1424:
	v_lshlrev_b32_e32 v0, 1, v4
	v_and_b32_e32 v236, 32, v0
	v_lshlrev_b32_e32 v0, 4, v4
	v_and_b32_e32 v0, 0xc0, v0
	v_lshl_or_b32 v234, v232, 8, v0
	v_add_u32_e32 v0, 0, v236
	v_add3_u32 v241, v0, v233, v234
	v_max3_f32 v0, v48, v49, v32
	v_max3_f32 v4, v50, v51, v33
	s_and_b32 s3, s3, 0x3fffffc0
	v_max3_f32 v0, v0, v34, v35
	v_max3_f32 v4, v4, v54, v55
	s_add_i32 s9, s25, 0x100
	v_max3_f32 v0, v0, v52, v53
	v_max3_f32 v4, v4, v38, v39
	s_lshl_b32 s3, s3, 2
	v_max3_f32 v0, v0, v36, v37
	v_max3_f32 v4, v4, v58, v59
	s_add_i32 s59, s3, 0
	v_max3_f32 v0, v0, v56, v57
	v_max3_f32 v4, v4, v42, v43
	s_lshr_b32 s3, s9, 6
	v_max3_f32 v0, v0, v40, v41
	v_max3_f32 v4, v4, v62, v63
	s_cmp_lg_u32 0, -1
	v_max3_f32 v0, v0, v60, v61
	v_max3_f32 v4, v4, v46, v47
	v_lshl_add_u64 v[214:215], v[2:3], 0, s[74:75]
	v_max3_f32 v0, v0, v44, v45
	s_mov_b32 s42, 1
	v_max_f32_e32 v0, v0, v4
	s_mov_b32 s50, 0
	v_mov_b32_e32 v4, v0
	s_nop 1
	v_permlane32_swap_b32_e32 v0, v4
	v_max_f32_e32 v0, v0, v4
	v_lshlrev_b32_e32 v242, 4, v232
	v_add_f32_e32 v239, v1, v0
	v_sub_f32_e32 v4, v48, v0
	v_sub_f32_e32 v5, v32, v0
	v_sub_f32_e32 v6, v49, v0
	v_sub_f32_e32 v7, v33, v0
	v_sub_f32_e32 v8, v50, v0
	s_nop 0
	v_xor_b32_e32 v64, 0x80000000, v239
	v_mov_b32_e32 v65, v64
	v_mov_b32_e32 v66, v64
	v_mov_b32_e32 v67, v64
	v_mov_b32_e32 v68, v64
	v_mov_b32_e32 v69, v64
	v_mov_b32_e32 v70, v64
	v_mov_b32_e32 v71, v64
	v_mov_b32_e32 v72, v64
	v_mov_b32_e32 v73, v64
	v_mov_b32_e32 v74, v64
	v_mov_b32_e32 v75, v64
	v_mov_b32_e32 v76, v64
	v_mov_b32_e32 v77, v64
	v_mov_b32_e32 v78, v64
	v_mov_b32_e32 v79, v64
	s_waitcnt vmcnt(0) lgkmcnt(0)
	s_barrier
	v_exp_f32_e32 v96, v4
	v_exp_f32_e32 v80, v5
	v_lshl_add_u64 v[4:5], v[212:213], 0, s[82:83]
	s_mov_b32 s9, m0
	s_mov_b32 m0, s66
	s_nop 0
	global_load_lds_dwordx4 v[4:5], off
	s_mov_b32 m0, s9
	s_cselect_b32 s9, 0, 0
	s_add_i32 s8, s9, s8
	s_add_i32 s8, s8, 0x8000
	s_mov_b32 s9, m0
	s_mov_b32 m0, s8
	s_nop 0
	global_load_lds_dwordx4 v[214:215], off
	s_mov_b32 m0, s9
	ds_read_b128 v[204:207], v240 offset:8192
	ds_read_b128 v[200:203], v240 offset:8704
	ds_read_b128 v[196:199], v240 offset:10240
	ds_read_b128 v[192:195], v240 offset:10752
	ds_read_b128 v[188:191], v240 offset:12288
	ds_read_b128 v[184:187], v240 offset:12800
	ds_read_b128 v[180:183], v240 offset:14336
	ds_read_b128 v[176:179], v240 offset:14848
	v_sub_f32_e32 v9, v34, v0
	v_sub_f32_e32 v10, v51, v0
	v_sub_f32_e32 v11, v35, v0
	v_sub_f32_e32 v12, v52, v0
	v_sub_f32_e32 v13, v36, v0
	v_sub_f32_e32 v14, v53, v0
	v_sub_f32_e32 v15, v37, v0
	v_sub_f32_e32 v32, v54, v0
	v_sub_f32_e32 v33, v38, v0
	v_sub_f32_e32 v34, v55, v0
	v_sub_f32_e32 v35, v39, v0
	v_sub_f32_e32 v36, v56, v0
	v_sub_f32_e32 v37, v40, v0
	v_sub_f32_e32 v38, v57, v0
	v_sub_f32_e32 v39, v41, v0
	v_sub_f32_e32 v40, v58, v0
	v_sub_f32_e32 v41, v42, v0
	v_sub_f32_e32 v42, v59, v0
	v_sub_f32_e32 v43, v43, v0
	v_sub_f32_e32 v48, v60, v0
	v_sub_f32_e32 v44, v44, v0
	v_sub_f32_e32 v49, v61, v0
	v_sub_f32_e32 v45, v45, v0
	v_sub_f32_e32 v50, v62, v0
	v_sub_f32_e32 v46, v46, v0
	v_sub_f32_e32 v51, v63, v0
	v_sub_f32_e32 v0, v47, v0
	v_exp_f32_e32 v97, v6
	v_exp_f32_e32 v98, v8
	v_exp_f32_e32 v99, v10
	v_exp_f32_e32 v100, v12
	v_exp_f32_e32 v101, v14
	v_exp_f32_e32 v102, v32
	v_exp_f32_e32 v103, v34
	v_exp_f32_e32 v104, v36
	v_exp_f32_e32 v105, v38
	v_exp_f32_e32 v106, v40
	v_exp_f32_e32 v107, v42
	v_exp_f32_e32 v108, v48
	v_exp_f32_e32 v109, v49
	v_exp_f32_e32 v110, v50
	v_exp_f32_e32 v111, v51
	v_exp_f32_e32 v81, v7
	v_exp_f32_e32 v82, v9
	v_exp_f32_e32 v83, v11
	v_exp_f32_e32 v84, v13
	v_exp_f32_e32 v85, v15
	v_exp_f32_e32 v86, v33
	v_exp_f32_e32 v87, v35
	v_exp_f32_e32 v88, v37
	v_exp_f32_e32 v89, v39
	v_exp_f32_e32 v90, v41
	v_exp_f32_e32 v91, v43
	v_exp_f32_e32 v92, v44
	v_exp_f32_e32 v93, v45
	v_exp_f32_e32 v94, v46
	v_exp_f32_e32 v95, v0
	s_waitcnt vmcnt(2) lgkmcnt(0)
	s_barrier
	s_andn2_b64 vcc, exec, s[0:1]
	v_cmp_gt_u32_e64 s[8:9], 32, v229
	v_lshl_add_u32 v237, v231, 2, s59
	s_cbranch_vccnz .LBB0_1440
	v_mov_b32_e32 v14, v1
	v_mov_b32_e32 v15, v1
	v_lshl_add_u64 v[216:217], v[2:3], 0, s[82:83]
	s_mov_b64 s[0:1], 0xa0000
	v_mov_b32_e32 v0, v1
	v_mov_b32_e32 v2, v1
	v_mov_b32_e32 v3, v1
	v_mov_b32_e32 v4, v1
	v_mov_b32_e32 v5, v1
	v_mov_b32_e32 v6, v1
	v_mov_b32_e32 v7, v1
	v_mov_b32_e32 v8, v1
	v_mov_b32_e32 v9, v1
	v_mov_b32_e32 v10, v1
	v_mov_b32_e32 v11, v1
	v_mov_b32_e32 v12, v1
	v_mov_b32_e32 v13, v1
	v_mov_b64_e32 v[62:63], v[14:15]
	v_mov_b64_e32 v[46:47], v[14:15]
	v_lshl_add_u64 v[218:219], v[212:213], 0, s[0:1]
	s_mov_b32 s0, 0
	s_movk_i32 s50, 0x4000
	s_movk_i32 s51, 0x2000
	v_mov_b32_e32 v243, 0
	s_mov_b32 s42, 6
	v_mov_b64_e32 v[60:61], v[12:13]
	v_mov_b64_e32 v[58:59], v[10:11]
	v_mov_b64_e32 v[56:57], v[8:9]
	v_mov_b64_e32 v[54:55], v[6:7]
	v_mov_b64_e32 v[52:53], v[4:5]
	v_mov_b64_e32 v[50:51], v[2:3]
	v_mov_b64_e32 v[48:49], v[0:1]
	v_mov_b64_e32 v[44:45], v[12:13]
	v_mov_b64_e32 v[42:43], v[10:11]
	v_mov_b64_e32 v[40:41], v[8:9]
	v_mov_b64_e32 v[38:39], v[6:7]
	v_mov_b64_e32 v[36:37], v[4:5]
	v_mov_b64_e32 v[34:35], v[2:3]
	v_mov_b64_e32 v[32:33], v[0:1]
	.p2align	6

;     __host__ __device__ bool next(int i, Unit& u) const { if (i >= 2) return false; u.pm = 32 * i + (v >> 3); u.pn = v & 7; return true; }
; template <class Epi, class Sched, bool ALIGN_EPI = false, bool SP2 = false>
; __device__ __forceinline__ void gemm_phase(PG8_LAS unsigned char* lds, const Gemm g, const Sched& S, const Epi& E) {
;     ...
;         const bool has_next = S.next(ui + 1, nxt);
;         const char* nA = has_next ? (const char*)g.A + (size_t)nxt.pm * tstep : cA; const char* nB = has_next ? (const char*)g.Bt + (size_t)nxt.pn * tstep : cB;
;         for (int t = 0; t < nt; t += 2) {
;             const bool last = (t == nt - 2);
;             const char* a1 = cA + (size_t)(t + 1) * kstep;
;             const char* a2 = last ? nA : cA + (size_t)(t + 2) * kstep; const char* b2 = last ? nB : cB + (size_t)(t + 2) * kstep;
;     ...
; #pragma unroll
;         for (int a = 0; a < 2; ++a)
; #pragma unroll
;             for (int b = 0; b < 2; ++b)
; #pragma unroll
;                 for (int m = 0; m < 4; ++m)
; #pragma unroll
;                     for (int n = 0; n < 2; ++n) acc[a][b][m][n] = (f32x4){0.f, 0.f, 0.f, 0.f};
.LBB0_1677:
	s_ashr_i32 s21, s20, 31
	s_lshl_b64 s[22:23], s[20:21], 19
	s_add_u32 s22, s26, s22
	s_addc_u32 s23, s27, s23
	s_and_b64 s[28:29], s[10:11], exec
	s_cselect_b32 s21, s23, s25
	s_cselect_b32 s51, s22, s24
	s_ashr_i32 s19, s18, 31
	s_lshl_b64 s[28:29], s[18:19], 19
	v_readlane_b32 s36, v250, 30
	v_readlane_b32 s37, v250, 31
	s_add_u32 s28, s36, s28
	s_addc_u32 s29, s37, s29
	s_and_b64 s[36:37], s[10:11], exec
	s_cselect_b32 s19, s29, s1
	s_cselect_b32 s52, s28, s0
	s_add_u32 s36, s24, 0x40080
	s_addc_u32 s37, s25, 0
	s_add_u32 s53, s0, 0x100
	v_mov_b32_e32 v0, 0
	s_addc_u32 s54, s1, 0
	s_mov_b32 s55, -2
	v_mov_b32_e32 v1, v0
	v_mov_b32_e32 v2, v0
	v_mov_b32_e32 v3, v0
	v_mov_b32_e32 v4, v0
	v_mov_b32_e32 v5, v0
	v_mov_b32_e32 v6, v0
	v_mov_b32_e32 v7, v0
	v_mov_b32_e32 v12, v0
	v_mov_b32_e32 v13, v0
	v_mov_b32_e32 v14, v0
	v_mov_b32_e32 v15, v0
	v_mov_b32_e32 v20, v0
	v_mov_b32_e32 v21, v0
	v_mov_b32_e32 v22, v0
	v_mov_b32_e32 v23, v0
	v_mov_b32_e32 v28, v0
	v_mov_b32_e32 v29, v0
	v_mov_b32_e32 v30, v0
	v_mov_b32_e32 v31, v0
	v_mov_b32_e32 v36, v0
	v_mov_b32_e32 v37, v0
	v_mov_b32_e32 v38, v0
	v_mov_b32_e32 v39, v0
	v_mov_b32_e32 v44, v0
	v_mov_b32_e32 v45, v0
	v_mov_b32_e32 v46, v0
	v_mov_b32_e32 v47, v0
	v_mov_b32_e32 v52, v0
	v_mov_b32_e32 v53, v0
	v_mov_b32_e32 v54, v0
	v_mov_b32_e32 v55, v0
	v_mov_b32_e32 v8, v0
	v_mov_b32_e32 v9, v0
	v_mov_b32_e32 v10, v0
	v_mov_b32_e32 v11, v0
	v_mov_b32_e32 v16, v0
	v_mov_b32_e32 v17, v0
	v_mov_b32_e32 v18, v0
	v_mov_b32_e32 v19, v0
	v_mov_b32_e32 v24, v0
	v_mov_b32_e32 v25, v0
	v_mov_b32_e32 v26, v0
	v_mov_b32_e32 v27, v0
	v_mov_b32_e32 v32, v0
	v_mov_b32_e32 v33, v0
	v_mov_b32_e32 v34, v0
	v_mov_b32_e32 v35, v0
	v_mov_b32_e32 v40, v0
	v_mov_b32_e32 v41, v0
	v_mov_b32_e32 v42, v0
	v_mov_b32_e32 v43, v0
	v_mov_b32_e32 v48, v0
	v_mov_b32_e32 v49, v0
	v_mov_b32_e32 v50, v0
	v_mov_b32_e32 v51, v0
	v_mov_b32_e32 v56, v0
	v_mov_b32_e32 v57, v0
	v_mov_b32_e32 v58, v0
	v_mov_b32_e32 v59, v0
	v_mov_b32_e32 v60, v0
	v_mov_b32_e32 v61, v0
	v_mov_b32_e32 v62, v0
	v_mov_b32_e32 v63, v0
	v_mov_b32_e32 v64, v0
	v_mov_b32_e32 v65, v0
	v_mov_b32_e32 v66, v0
	v_mov_b32_e32 v67, v0
	v_mov_b32_e32 v68, v0
	v_mov_b32_e32 v69, v0
	v_mov_b32_e32 v70, v0
	v_mov_b32_e32 v71, v0
	v_mov_b32_e32 v76, v0
	v_mov_b32_e32 v77, v0
	v_mov_b32_e32 v78, v0
	v_mov_b32_e32 v79, v0
	v_mov_b32_e32 v84, v0
	v_mov_b32_e32 v85, v0
	v_mov_b32_e32 v86, v0
	v_mov_b32_e32 v87, v0
	v_mov_b32_e32 v92, v0
	v_mov_b32_e32 v93, v0
	v_mov_b32_e32 v94, v0
	v_mov_b32_e32 v95, v0
	v_mov_b32_e32 v100, v0
	v_mov_b32_e32 v101, v0
	v_mov_b32_e32 v102, v0
	v_mov_b32_e32 v103, v0
	v_mov_b32_e32 v104, v0
	v_mov_b32_e32 v105, v0
	v_mov_b32_e32 v106, v0
	v_mov_b32_e32 v107, v0
	v_mov_b32_e32 v112, v0
	v_mov_b32_e32 v113, v0
	v_mov_b32_e32 v114, v0
	v_mov_b32_e32 v115, v0
	v_mov_b32_e32 v72, v0
	v_mov_b32_e32 v73, v0
	v_mov_b32_e32 v74, v0
	v_mov_b32_e32 v75, v0
	v_mov_b32_e32 v80, v0
	v_mov_b32_e32 v81, v0
	v_mov_b32_e32 v82, v0
	v_mov_b32_e32 v83, v0
	v_mov_b32_e32 v88, v0
	v_mov_b32_e32 v89, v0
	v_mov_b32_e32 v90, v0
	v_mov_b32_e32 v91, v0
	v_mov_b32_e32 v96, v0
	v_mov_b32_e32 v97, v0
	v_mov_b32_e32 v98, v0
	v_mov_b32_e32 v99, v0
	v_mov_b32_e32 v108, v0
	v_mov_b32_e32 v109, v0
	v_mov_b32_e32 v110, v0
	v_mov_b32_e32 v111, v0
	v_mov_b32_e32 v116, v0
	v_mov_b32_e32 v117, v0
	v_mov_b32_e32 v118, v0
	v_mov_b32_e32 v119, v0
	v_mov_b32_e32 v120, v0
	v_mov_b32_e32 v121, v0
	v_mov_b32_e32 v122, v0
	v_mov_b32_e32 v123, v0
	v_mov_b32_e32 v124, v0
	v_mov_b32_e32 v125, v0
	v_mov_b32_e32 v126, v0
	v_mov_b32_e32 v127, v0
	.p2align	6

;     __host__ __device__ bool next(int i, Unit& u) const { if (i >= 2) return false; u.pm = 32 * i + (v >> 3); u.pn = v & 7; return true; }
; template <class Epi, class Sched, bool ALIGN_EPI = false, bool SP2 = false>
; __device__ __forceinline__ void gemm_phase(PG8_LAS unsigned char* lds, const Gemm g, const Sched& S, const Epi& E) {
;     ...
;         const bool has_next = S.next(ui + 1, nxt);
;         const char* nA = has_next ? (const char*)g.A + (size_t)nxt.pm * tstep : cA; const char* nB = has_next ? (const char*)g.Bt + (size_t)nxt.pn * tstep : cB;
;         for (int t = 0; t < nt; t += 2) {
;             const bool last = (t == nt - 2);
;             const char* a1 = cA + (size_t)(t + 1) * kstep;
;             const char* a2 = last ? nA : cA + (size_t)(t + 2) * kstep; const char* b2 = last ? nB : cB + (size_t)(t + 2) * kstep;
;     ...
; #pragma unroll
;         for (int a = 0; a < 2; ++a)
; #pragma unroll
;             for (int b = 0; b < 2; ++b)
; #pragma unroll
;                 for (int m = 0; m < 4; ++m)
; #pragma unroll
;                     for (int n = 0; n < 2; ++n) acc[a][b][m][n] = (f32x4){0.f, 0.f, 0.f, 0.f};
.LBB0_1701:
	s_ashr_i32 s23, s22, 31
	s_lshl_b64 s[28:29], s[22:23], 19
	s_add_u32 s28, s46, s28
	s_addc_u32 s29, s47, s29
	s_and_b64 s[30:31], s[10:11], exec
	s_cselect_b32 s23, s29, s25
	s_cselect_b32 s53, s28, s24
	s_ashr_i32 s21, s20, 31
	s_lshl_b64 s[30:31], s[20:21], 19
	v_readlane_b32 s38, v250, 28
	v_readlane_b32 s39, v250, 29
	s_add_u32 s30, s38, s30
	s_addc_u32 s31, s39, s31
	s_and_b64 s[38:39], s[10:11], exec
	s_cselect_b32 s21, s31, s1
	s_cselect_b32 s54, s30, s0
	s_add_u32 s38, s24, 0x40080
	s_addc_u32 s39, s25, 0
	s_add_u32 s55, s0, 0x100
	v_mov_b32_e32 v0, 0
	s_addc_u32 s56, s1, 0
	s_mov_b32 s57, -2
	v_mov_b32_e32 v1, v0
	v_mov_b32_e32 v2, v0
	v_mov_b32_e32 v3, v0
	v_mov_b32_e32 v4, v0
	v_mov_b32_e32 v5, v0
	v_mov_b32_e32 v6, v0
	v_mov_b32_e32 v7, v0
	v_mov_b32_e32 v16, v0
	v_mov_b32_e32 v17, v0
	v_mov_b32_e32 v18, v0
	v_mov_b32_e32 v19, v0
	v_mov_b32_e32 v20, v0
	v_mov_b32_e32 v21, v0
	v_mov_b32_e32 v22, v0
	v_mov_b32_e32 v23, v0
	v_mov_b32_e32 v32, v0
	v_mov_b32_e32 v33, v0
	v_mov_b32_e32 v34, v0
	v_mov_b32_e32 v35, v0
	v_mov_b32_e32 v36, v0
	v_mov_b32_e32 v37, v0
	v_mov_b32_e32 v38, v0
	v_mov_b32_e32 v39, v0
	v_mov_b32_e32 v48, v0
	v_mov_b32_e32 v49, v0
	v_mov_b32_e32 v50, v0
	v_mov_b32_e32 v51, v0
	v_mov_b32_e32 v52, v0
	v_mov_b32_e32 v53, v0
	v_mov_b32_e32 v54, v0
	v_mov_b32_e32 v55, v0
	v_mov_b32_e32 v8, v0
	v_mov_b32_e32 v9, v0
	v_mov_b32_e32 v10, v0
	v_mov_b32_e32 v11, v0
	v_mov_b32_e32 v12, v0
	v_mov_b32_e32 v13, v0
	v_mov_b32_e32 v14, v0
	v_mov_b32_e32 v15, v0
	v_mov_b32_e32 v24, v0
	v_mov_b32_e32 v25, v0
	v_mov_b32_e32 v26, v0
	v_mov_b32_e32 v27, v0
	v_mov_b32_e32 v28, v0
	v_mov_b32_e32 v29, v0
	v_mov_b32_e32 v30, v0
	v_mov_b32_e32 v31, v0
	v_mov_b32_e32 v40, v0
	v_mov_b32_e32 v41, v0
	v_mov_b32_e32 v42, v0
	v_mov_b32_e32 v43, v0
	v_mov_b32_e32 v44, v0
	v_mov_b32_e32 v45, v0
	v_mov_b32_e32 v46, v0
	v_mov_b32_e32 v47, v0
	v_mov_b32_e32 v56, v0
	v_mov_b32_e32 v57, v0
	v_mov_b32_e32 v58, v0
	v_mov_b32_e32 v59, v0
	v_mov_b32_e32 v60, v0
	v_mov_b32_e32 v61, v0
	v_mov_b32_e32 v62, v0
	v_mov_b32_e32 v63, v0
	v_mov_b32_e32 v64, v0
	v_mov_b32_e32 v65, v0
	v_mov_b32_e32 v66, v0
	v_mov_b32_e32 v67, v0
	v_mov_b32_e32 v68, v0
	v_mov_b32_e32 v69, v0
	v_mov_b32_e32 v70, v0
	v_mov_b32_e32 v71, v0
	v_mov_b32_e32 v80, v0
	v_mov_b32_e32 v81, v0
	v_mov_b32_e32 v82, v0
	v_mov_b32_e32 v83, v0
	v_mov_b32_e32 v84, v0
	v_mov_b32_e32 v85, v0
	v_mov_b32_e32 v86, v0
	v_mov_b32_e32 v87, v0
	v_mov_b32_e32 v96, v0
	v_mov_b32_e32 v97, v0
	v_mov_b32_e32 v98, v0
	v_mov_b32_e32 v99, v0
	v_mov_b32_e32 v100, v0
	v_mov_b32_e32 v101, v0
	v_mov_b32_e32 v102, v0
	v_mov_b32_e32 v103, v0
	v_mov_b32_e32 v112, v0
	v_mov_b32_e32 v113, v0
	v_mov_b32_e32 v114, v0
	v_mov_b32_e32 v115, v0
	v_mov_b32_e32 v116, v0
	v_mov_b32_e32 v117, v0
	v_mov_b32_e32 v118, v0
	v_mov_b32_e32 v119, v0
	v_mov_b32_e32 v72, v0
	v_mov_b32_e32 v73, v0
	v_mov_b32_e32 v74, v0
	v_mov_b32_e32 v75, v0
	v_mov_b32_e32 v76, v0
	v_mov_b32_e32 v77, v0
	v_mov_b32_e32 v78, v0
	v_mov_b32_e32 v79, v0
	v_mov_b32_e32 v88, v0
	v_mov_b32_e32 v89, v0
	v_mov_b32_e32 v90, v0
	v_mov_b32_e32 v91, v0
	v_mov_b32_e32 v92, v0
	v_mov_b32_e32 v93, v0
	v_mov_b32_e32 v94, v0
	v_mov_b32_e32 v95, v0
	v_mov_b32_e32 v104, v0
	v_mov_b32_e32 v105, v0
	v_mov_b32_e32 v106, v0
	v_mov_b32_e32 v107, v0
	v_mov_b32_e32 v108, v0
	v_mov_b32_e32 v109, v0
	v_mov_b32_e32 v110, v0
	v_mov_b32_e32 v111, v0
	v_mov_b32_e32 v120, v0
	v_mov_b32_e32 v121, v0
	v_mov_b32_e32 v122, v0
	v_mov_b32_e32 v123, v0
	v_mov_b32_e32 v124, v0
	v_mov_b32_e32 v125, v0
	v_mov_b32_e32 v126, v0
	v_mov_b32_e32 v127, v0
	.p2align	6

;     __host__ __device__ bool next(int i, Unit& u) const { if (i >= 2) return false; u.pm = 32 * i + (v >> 3); u.pn = v & 7; return true; }
; template <class Epi, class Sched, bool ALIGN_EPI = false, bool SP2 = false>
; __device__ __forceinline__ void gemm_phase(PG8_LAS unsigned char* lds, const Gemm g, const Sched& S, const Epi& E) {
;     ...
;         const bool has_next = S.next(ui + 1, nxt);
;         const char* nA = has_next ? (const char*)g.A + (size_t)nxt.pm * tstep : cA; const char* nB = has_next ? (const char*)g.Bt + (size_t)nxt.pn * tstep : cB;
;         for (int t = 0; t < nt; t += 2) {
;             const bool last = (t == nt - 2);
;             const char* a1 = cA + (size_t)(t + 1) * kstep;
;             const char* a2 = last ? nA : cA + (size_t)(t + 2) * kstep; const char* b2 = last ? nB : cB + (size_t)(t + 2) * kstep;
;     ...
; #pragma unroll
;         for (int a = 0; a < 2; ++a)
; #pragma unroll
;             for (int b = 0; b < 2; ++b)
; #pragma unroll
;                 for (int m = 0; m < 4; ++m)
; #pragma unroll
;                     for (int n = 0; n < 2; ++n) acc[a][b][m][n] = (f32x4){0.f, 0.f, 0.f, 0.f};
.LBB0_1797:
	s_ashr_i32 s23, s22, 31
	s_lshl_b64 s[28:29], s[22:23], 20
	s_add_u32 s28, s6, s28
	s_addc_u32 s29, s7, s29
	s_and_b64 s[30:31], s[10:11], exec
	s_cselect_b32 s23, s29, s25
	s_cselect_b32 s52, s28, s24
	s_ashr_i32 s21, s20, 31
	s_lshl_b64 s[30:31], s[20:21], 20
	s_add_u32 s30, s72, s30
	s_addc_u32 s31, s73, s31
	s_and_b64 s[40:41], s[10:11], exec
	s_cselect_b32 s21, s31, s1
	s_cselect_b32 s53, s30, s0
	s_add_u32 s40, s24, 0x80080
	s_addc_u32 s41, s25, 0
	s_add_u32 s54, s0, 0x100
	v_mov_b32_e32 v0, 0
	s_addc_u32 s55, s1, 0
	s_mov_b32 s56, -2
	s_waitcnt lgkmcnt(0)
	v_mov_b32_e32 v1, v0
	v_mov_b32_e32 v2, v0
	v_mov_b32_e32 v3, v0
	v_mov_b32_e32 v4, v0
	v_mov_b32_e32 v5, v0
	v_mov_b32_e32 v6, v0
	v_mov_b32_e32 v7, v0
	v_mov_b32_e32 v16, v0
	v_mov_b32_e32 v17, v0
	v_mov_b32_e32 v18, v0
	v_mov_b32_e32 v19, v0
	v_mov_b32_e32 v20, v0
	v_mov_b32_e32 v21, v0
	v_mov_b32_e32 v22, v0
	v_mov_b32_e32 v23, v0
	v_mov_b32_e32 v32, v0
	v_mov_b32_e32 v33, v0
	v_mov_b32_e32 v34, v0
	v_mov_b32_e32 v35, v0
	v_mov_b32_e32 v36, v0
	v_mov_b32_e32 v37, v0
	v_mov_b32_e32 v38, v0
	v_mov_b32_e32 v39, v0
	v_mov_b32_e32 v48, v0
	v_mov_b32_e32 v49, v0
	v_mov_b32_e32 v50, v0
	v_mov_b32_e32 v51, v0
	v_mov_b32_e32 v52, v0
	v_mov_b32_e32 v53, v0
	v_mov_b32_e32 v54, v0
	v_mov_b32_e32 v55, v0
	v_mov_b32_e32 v8, v0
	v_mov_b32_e32 v9, v0
	v_mov_b32_e32 v10, v0
	v_mov_b32_e32 v11, v0
	v_mov_b32_e32 v12, v0
	v_mov_b32_e32 v13, v0
	v_mov_b32_e32 v14, v0
	v_mov_b32_e32 v15, v0
	v_mov_b32_e32 v24, v0
	v_mov_b32_e32 v25, v0
	v_mov_b32_e32 v26, v0
	v_mov_b32_e32 v27, v0
	v_mov_b32_e32 v28, v0
	v_mov_b32_e32 v29, v0
	v_mov_b32_e32 v30, v0
	v_mov_b32_e32 v31, v0
	v_mov_b32_e32 v40, v0
	v_mov_b32_e32 v41, v0
	v_mov_b32_e32 v42, v0
	v_mov_b32_e32 v43, v0
	v_mov_b32_e32 v44, v0
	v_mov_b32_e32 v45, v0
	v_mov_b32_e32 v46, v0
	v_mov_b32_e32 v47, v0
	v_mov_b32_e32 v56, v0
	v_mov_b32_e32 v57, v0
	v_mov_b32_e32 v58, v0
	v_mov_b32_e32 v59, v0
	v_mov_b32_e32 v60, v0
	v_mov_b32_e32 v61, v0
	v_mov_b32_e32 v62, v0
	v_mov_b32_e32 v63, v0
	v_mov_b32_e32 v64, v0
	v_mov_b32_e32 v65, v0
	v_mov_b32_e32 v66, v0
	v_mov_b32_e32 v67, v0
	v_mov_b32_e32 v68, v0
	v_mov_b32_e32 v69, v0
	v_mov_b32_e32 v70, v0
	v_mov_b32_e32 v71, v0
	v_mov_b32_e32 v80, v0
	v_mov_b32_e32 v81, v0
	v_mov_b32_e32 v82, v0
	v_mov_b32_e32 v83, v0
	v_mov_b32_e32 v84, v0
	v_mov_b32_e32 v85, v0
	v_mov_b32_e32 v86, v0
	v_mov_b32_e32 v87, v0
	v_mov_b32_e32 v96, v0
	v_mov_b32_e32 v97, v0
	v_mov_b32_e32 v98, v0
	v_mov_b32_e32 v99, v0
	v_mov_b32_e32 v100, v0
	v_mov_b32_e32 v101, v0
	v_mov_b32_e32 v102, v0
	v_mov_b32_e32 v103, v0
	v_mov_b32_e32 v112, v0
	v_mov_b32_e32 v113, v0
	v_mov_b32_e32 v114, v0
	v_mov_b32_e32 v115, v0
	v_mov_b32_e32 v116, v0
	v_mov_b32_e32 v117, v0
	v_mov_b32_e32 v118, v0
	v_mov_b32_e32 v119, v0
	v_mov_b32_e32 v72, v0
	v_mov_b32_e32 v73, v0
	v_mov_b32_e32 v74, v0
	v_mov_b32_e32 v75, v0
	v_mov_b32_e32 v76, v0
	v_mov_b32_e32 v77, v0
	v_mov_b32_e32 v78, v0
	v_mov_b32_e32 v79, v0
	v_mov_b32_e32 v88, v0
	v_mov_b32_e32 v89, v0
	v_mov_b32_e32 v90, v0
	v_mov_b32_e32 v91, v0
	v_mov_b32_e32 v92, v0
	v_mov_b32_e32 v93, v0
	v_mov_b32_e32 v94, v0
	v_mov_b32_e32 v95, v0
	v_mov_b32_e32 v104, v0
	v_mov_b32_e32 v105, v0
	v_mov_b32_e32 v106, v0
	v_mov_b32_e32 v107, v0
	v_mov_b32_e32 v108, v0
	v_mov_b32_e32 v109, v0
	v_mov_b32_e32 v110, v0
	v_mov_b32_e32 v111, v0
	v_mov_b32_e32 v120, v0
	v_mov_b32_e32 v121, v0
	v_mov_b32_e32 v122, v0
	v_mov_b32_e32 v123, v0
	v_mov_b32_e32 v124, v0
	v_mov_b32_e32 v125, v0
	v_mov_b32_e32 v126, v0
	v_mov_b32_e32 v127, v0
	.p2align	6

;     __host__ __device__ bool next(int i, Unit& u) const { if (i >= 2) return false; u.pm = 32 * i + (v >> 3); u.pn = v & 7; return true; }
; template <class Epi, class Sched, bool ALIGN_EPI = false, bool SP2 = false>
; __device__ __forceinline__ void gemm_phase(PG8_LAS unsigned char* lds, const Gemm g, const Sched& S, const Epi& E) {
;     ...
;         const bool has_next = S.next(ui + 1, nxt);
;         const char* nA = has_next ? (const char*)g.A + (size_t)nxt.pm * tstep : cA; const char* nB = has_next ? (const char*)g.Bt + (size_t)nxt.pn * tstep : cB;
;         for (int t = 0; t < nt; t += 2) {
;             const bool last = (t == nt - 2);
;             const char* a1 = cA + (size_t)(t + 1) * kstep;
;             const char* a2 = last ? nA : cA + (size_t)(t + 2) * kstep; const char* b2 = last ? nB : cB + (size_t)(t + 2) * kstep;
;     ...
; #pragma unroll
;         for (int a = 0; a < 2; ++a)
; #pragma unroll
;             for (int b = 0; b < 2; ++b)
; #pragma unroll
;                 for (int m = 0; m < 4; ++m)
; #pragma unroll
;                     for (int n = 0; n < 2; ++n) acc[a][b][m][n] = (f32x4){0.f, 0.f, 0.f, 0.f};
.LBB0_1881:
	s_ashr_i32 s21, s20, 31
	s_lshl_b64 s[22:23], s[20:21], 20
	s_add_u32 s22, s70, s22
	s_addc_u32 s23, s71, s23
	s_and_b64 s[28:29], s[4:5], exec
	s_cselect_b32 s21, s23, s25
	s_cselect_b32 s51, s22, s24
	s_ashr_i32 s19, s18, 31
	s_lshl_b64 s[28:29], s[18:19], 20
	v_readlane_b32 s30, v250, 4
	v_readlane_b32 s31, v250, 5
	s_add_u32 s28, s30, s28
	s_addc_u32 s29, s31, s29
	s_and_b64 s[30:31], s[4:5], exec
	s_cselect_b32 s19, s29, s1
	s_cselect_b32 s52, s28, s0
	s_add_u32 s30, s24, 0x80080
	s_addc_u32 s31, s25, 0
	s_add_u32 s53, s0, 0x100
	v_mov_b32_e32 v0, 0
	s_addc_u32 s54, s1, 0
	s_mov_b32 s55, -2
	v_mov_b32_e32 v1, v0
	v_mov_b32_e32 v2, v0
	v_mov_b32_e32 v3, v0
	v_mov_b32_e32 v4, v0
	v_mov_b32_e32 v5, v0
	v_mov_b32_e32 v6, v0
	v_mov_b32_e32 v7, v0
	v_mov_b32_e32 v16, v0
	v_mov_b32_e32 v17, v0
	v_mov_b32_e32 v18, v0
	v_mov_b32_e32 v19, v0
	v_mov_b32_e32 v20, v0
	v_mov_b32_e32 v21, v0
	v_mov_b32_e32 v22, v0
	v_mov_b32_e32 v23, v0
	v_mov_b32_e32 v32, v0
	v_mov_b32_e32 v33, v0
	v_mov_b32_e32 v34, v0
	v_mov_b32_e32 v35, v0
	v_mov_b32_e32 v36, v0
	v_mov_b32_e32 v37, v0
	v_mov_b32_e32 v38, v0
	v_mov_b32_e32 v39, v0
	v_mov_b32_e32 v48, v0
	v_mov_b32_e32 v49, v0
	v_mov_b32_e32 v50, v0
	v_mov_b32_e32 v51, v0
	v_mov_b32_e32 v52, v0
	v_mov_b32_e32 v53, v0
	v_mov_b32_e32 v54, v0
	v_mov_b32_e32 v55, v0
	v_mov_b32_e32 v8, v0
	v_mov_b32_e32 v9, v0
	v_mov_b32_e32 v10, v0
	v_mov_b32_e32 v11, v0
	v_mov_b32_e32 v12, v0
	v_mov_b32_e32 v13, v0
	v_mov_b32_e32 v14, v0
	v_mov_b32_e32 v15, v0
	v_mov_b32_e32 v24, v0
	v_mov_b32_e32 v25, v0
	v_mov_b32_e32 v26, v0
	v_mov_b32_e32 v27, v0
	v_mov_b32_e32 v28, v0
	v_mov_b32_e32 v29, v0
	v_mov_b32_e32 v30, v0
	v_mov_b32_e32 v31, v0
	v_mov_b32_e32 v40, v0
	v_mov_b32_e32 v41, v0
	v_mov_b32_e32 v42, v0
	v_mov_b32_e32 v43, v0
	v_mov_b32_e32 v44, v0
	v_mov_b32_e32 v45, v0
	v_mov_b32_e32 v46, v0
	v_mov_b32_e32 v47, v0
	v_mov_b32_e32 v56, v0
	v_mov_b32_e32 v57, v0
	v_mov_b32_e32 v58, v0
	v_mov_b32_e32 v59, v0
	v_mov_b32_e32 v60, v0
	v_mov_b32_e32 v61, v0
	v_mov_b32_e32 v62, v0
	v_mov_b32_e32 v63, v0
	v_mov_b32_e32 v64, v0
	v_mov_b32_e32 v65, v0
	v_mov_b32_e32 v66, v0
	v_mov_b32_e32 v67, v0
	v_mov_b32_e32 v68, v0
	v_mov_b32_e32 v69, v0
	v_mov_b32_e32 v70, v0
	v_mov_b32_e32 v71, v0
	v_mov_b32_e32 v80, v0
	v_mov_b32_e32 v81, v0
	v_mov_b32_e32 v82, v0
	v_mov_b32_e32 v83, v0
	v_mov_b32_e32 v84, v0
	v_mov_b32_e32 v85, v0
	v_mov_b32_e32 v86, v0
	v_mov_b32_e32 v87, v0
	v_mov_b32_e32 v96, v0
	v_mov_b32_e32 v97, v0
	v_mov_b32_e32 v98, v0
	v_mov_b32_e32 v99, v0
	v_mov_b32_e32 v100, v0
	v_mov_b32_e32 v101, v0
	v_mov_b32_e32 v102, v0
	v_mov_b32_e32 v103, v0
	v_mov_b32_e32 v112, v0
	v_mov_b32_e32 v113, v0
	v_mov_b32_e32 v114, v0
	v_mov_b32_e32 v115, v0
	v_mov_b32_e32 v116, v0
	v_mov_b32_e32 v117, v0
	v_mov_b32_e32 v118, v0
	v_mov_b32_e32 v119, v0
	v_mov_b32_e32 v72, v0
	v_mov_b32_e32 v73, v0
	v_mov_b32_e32 v74, v0
	v_mov_b32_e32 v75, v0
	v_mov_b32_e32 v76, v0
	v_mov_b32_e32 v77, v0
	v_mov_b32_e32 v78, v0
	v_mov_b32_e32 v79, v0
	v_mov_b32_e32 v88, v0
	v_mov_b32_e32 v89, v0
	v_mov_b32_e32 v90, v0
	v_mov_b32_e32 v91, v0
	v_mov_b32_e32 v92, v0
	v_mov_b32_e32 v93, v0
	v_mov_b32_e32 v94, v0
	v_mov_b32_e32 v95, v0
	v_mov_b32_e32 v104, v0
	v_mov_b32_e32 v105, v0
	v_mov_b32_e32 v106, v0
	v_mov_b32_e32 v107, v0
	v_mov_b32_e32 v108, v0
	v_mov_b32_e32 v109, v0
	v_mov_b32_e32 v110, v0
	v_mov_b32_e32 v111, v0
	v_mov_b32_e32 v120, v0
	v_mov_b32_e32 v121, v0
	v_mov_b32_e32 v122, v0
	v_mov_b32_e32 v123, v0
	v_mov_b32_e32 v124, v0
	v_mov_b32_e32 v125, v0
	v_mov_b32_e32 v126, v0
	v_mov_b32_e32 v127, v0
	.p2align	6

;     __host__ __device__ bool next(int i, Unit& u) const { if (i >= 2) return false; u.pm = 32 * i + (v >> 3); u.pn = v & 7; return true; }
; template <class Epi, class Sched, bool ALIGN_EPI = false, bool SP2 = false>
; __device__ __forceinline__ void gemm_phase(PG8_LAS unsigned char* lds, const Gemm g, const Sched& S, const Epi& E) {
;     ...
;         const bool has_next = S.next(ui + 1, nxt);
;         const char* nA = has_next ? (const char*)g.A + (size_t)nxt.pm * tstep : cA; const char* nB = has_next ? (const char*)g.Bt + (size_t)nxt.pn * tstep : cB;
;         for (int t = 0; t < nt; t += 2) {
;             const bool last = (t == nt - 2);
;             const char* a1 = cA + (size_t)(t + 1) * kstep;
;             const char* a2 = last ? nA : cA + (size_t)(t + 2) * kstep; const char* b2 = last ? nB : cB + (size_t)(t + 2) * kstep;
;     ...
; #pragma unroll
;         for (int a = 0; a < 2; ++a)
; #pragma unroll
;             for (int b = 0; b < 2; ++b)
; #pragma unroll
;                 for (int m = 0; m < 4; ++m)
; #pragma unroll
;                     for (int n = 0; n < 2; ++n) acc[a][b][m][n] = (f32x4){0.f, 0.f, 0.f, 0.f};
.LBB0_2052:
	v_mov_b32_e32 v0, 0
	s_mov_b32 s55, -2
	s_mov_b64 s[6:7], s[18:19]
	v_mov_b32_e32 v1, v0
	v_mov_b32_e32 v2, v0
	v_mov_b32_e32 v3, v0
	v_mov_b32_e32 v4, v0
	v_mov_b32_e32 v5, v0
	v_mov_b32_e32 v6, v0
	v_mov_b32_e32 v7, v0
	v_mov_b32_e32 v12, v0
	v_mov_b32_e32 v13, v0
	v_mov_b32_e32 v14, v0
	v_mov_b32_e32 v15, v0
	v_mov_b32_e32 v20, v0
	v_mov_b32_e32 v21, v0
	v_mov_b32_e32 v22, v0
	v_mov_b32_e32 v23, v0
	v_mov_b32_e32 v28, v0
	v_mov_b32_e32 v29, v0
	v_mov_b32_e32 v30, v0
	v_mov_b32_e32 v31, v0
	v_mov_b32_e32 v36, v0
	v_mov_b32_e32 v37, v0
	v_mov_b32_e32 v38, v0
	v_mov_b32_e32 v39, v0
	v_mov_b32_e32 v48, v0
	v_mov_b32_e32 v49, v0
	v_mov_b32_e32 v50, v0
	v_mov_b32_e32 v51, v0
	v_mov_b32_e32 v52, v0
	v_mov_b32_e32 v53, v0
	v_mov_b32_e32 v54, v0
	v_mov_b32_e32 v55, v0
	v_mov_b32_e32 v8, v0
	v_mov_b32_e32 v9, v0
	v_mov_b32_e32 v10, v0
	v_mov_b32_e32 v11, v0
	v_mov_b32_e32 v16, v0
	v_mov_b32_e32 v17, v0
	v_mov_b32_e32 v18, v0
	v_mov_b32_e32 v19, v0
	v_mov_b32_e32 v24, v0
	v_mov_b32_e32 v25, v0
	v_mov_b32_e32 v26, v0
	v_mov_b32_e32 v27, v0
	v_mov_b32_e32 v32, v0
	v_mov_b32_e32 v33, v0
	v_mov_b32_e32 v34, v0
	v_mov_b32_e32 v35, v0
	v_mov_b32_e32 v40, v0
	v_mov_b32_e32 v41, v0
	v_mov_b32_e32 v42, v0
	v_mov_b32_e32 v43, v0
	v_mov_b32_e32 v44, v0
	v_mov_b32_e32 v45, v0
	v_mov_b32_e32 v46, v0
	v_mov_b32_e32 v47, v0
	v_mov_b32_e32 v56, v0
	v_mov_b32_e32 v57, v0
	v_mov_b32_e32 v58, v0
	v_mov_b32_e32 v59, v0
	v_mov_b32_e32 v60, v0
	v_mov_b32_e32 v61, v0
	v_mov_b32_e32 v62, v0
	v_mov_b32_e32 v63, v0
	v_mov_b32_e32 v64, v0
	v_mov_b32_e32 v65, v0
	v_mov_b32_e32 v66, v0
	v_mov_b32_e32 v67, v0
	v_mov_b32_e32 v68, v0
	v_mov_b32_e32 v69, v0
	v_mov_b32_e32 v70, v0
	v_mov_b32_e32 v71, v0
	v_mov_b32_e32 v76, v0
	v_mov_b32_e32 v77, v0
	v_mov_b32_e32 v78, v0
	v_mov_b32_e32 v79, v0
	v_mov_b32_e32 v84, v0
	v_mov_b32_e32 v85, v0
	v_mov_b32_e32 v86, v0
	v_mov_b32_e32 v87, v0
	v_mov_b32_e32 v92, v0
	v_mov_b32_e32 v93, v0
	v_mov_b32_e32 v94, v0
	v_mov_b32_e32 v95, v0
	v_mov_b32_e32 v100, v0
	v_mov_b32_e32 v101, v0
	v_mov_b32_e32 v102, v0
	v_mov_b32_e32 v103, v0
	v_mov_b32_e32 v112, v0
	v_mov_b32_e32 v113, v0
	v_mov_b32_e32 v114, v0
	v_mov_b32_e32 v115, v0
	v_mov_b32_e32 v116, v0
	v_mov_b32_e32 v117, v0
	v_mov_b32_e32 v118, v0
	v_mov_b32_e32 v119, v0
	v_mov_b32_e32 v72, v0
	v_mov_b32_e32 v73, v0
	v_mov_b32_e32 v74, v0
	v_mov_b32_e32 v75, v0
	v_mov_b32_e32 v80, v0
	v_mov_b32_e32 v81, v0
	v_mov_b32_e32 v82, v0
	v_mov_b32_e32 v83, v0
	v_mov_b32_e32 v88, v0
	v_mov_b32_e32 v89, v0
	v_mov_b32_e32 v90, v0
	v_mov_b32_e32 v91, v0
	v_mov_b32_e32 v96, v0
	v_mov_b32_e32 v97, v0
	v_mov_b32_e32 v98, v0
	v_mov_b32_e32 v99, v0
	v_mov_b32_e32 v104, v0
	v_mov_b32_e32 v105, v0
	v_mov_b32_e32 v106, v0
	v_mov_b32_e32 v107, v0
	v_mov_b32_e32 v108, v0
	v_mov_b32_e32 v109, v0
	v_mov_b32_e32 v110, v0
	v_mov_b32_e32 v111, v0
	v_mov_b32_e32 v120, v0
	v_mov_b32_e32 v121, v0
	v_mov_b32_e32 v122, v0
	v_mov_b32_e32 v123, v0
	v_mov_b32_e32 v124, v0
	v_mov_b32_e32 v125, v0
	v_mov_b32_e32 v126, v0
	v_mov_b32_e32 v127, v0
	.p2align	6
